# attention trailing half at s_setprio 3 instead of 1
# baseline (speedup 1.0000x reference)
; #define ATT_DMA2(src, tile, dstoff) do { int t_ = (tile); t_ = t_ < t_hi ? t_ : t_hi; glds2k((src) + (size_t)t_ * SLOT, lane16, (unsigned)(dstoff)); } while (0)
; __device__ __forceinline__ UnitDesc decode_unit(int idx, float Bn, float Cn, const __attribute__((address_space(3))) unsigned short* pre, const __attribute__((address_space(3))) unsigned short* sidx) {
;     ...
;     const unsigned it_ = (unsigned)__builtin_amdgcn_readfirstlane((int)((const __attribute__((address_space(3))) unsigned*)((const __attribute__((address_space(3))) unsigned char*)pre + ITEM_FROM_PRE))[idx]);
;     d.u = (int)(it_ & 511u); d.ci = (int)((it_ >> 10) & 3u); d.nc = (int)((it_ >> 12) & 3u); d.sid = __builtin_amdgcn_readfirstlane((int)sidx[d.u]);
;     const int k = d.u & 127; d.h = 3 - (d.u >> 7); d.qb = (k & 1) ? 63 - (k >> 1) : 64 + (k >> 1);
;     d.slope = exp2f(-2.f * (float)(d.h + 1));
;     const int R = __builtin_amdgcn_readfirstlane((int)((const __attribute__((address_space(3))) unsigned short*)((const __attribute__((address_space(3))) unsigned char*)pre + RTAB_FROM_PRE))[d.u]);
;     const int q0 = d.qb * 128; const int klo = q0 - R < 0 ? 0 : q0 - R, khi = q0 + 127 + R > M - 1 ? M - 1 : q0 + 127 + R;
;     const int tlo = klo >> 6, nt = (khi >> 6) - tlo + 1, base = nt / d.nc, rem = nt - base * d.nc;
;     d.t_lo = tlo + d.ci * base + (d.ci < rem ? d.ci : rem); d.t_hi = d.t_lo + base + (d.ci < rem ? 1 : 0) - 1;
; __device__ __forceinline__ void attn_unit(int idx, float Bn, float Cn, float lam, const __attribute__((address_space(3))) unsigned short* pre, const __attribute__((address_space(3))) unsigned short* sidx, ...
;     ...
;     const unsigned char* ksrc = Kimg + (size_t)h * 256 * SLOT + wid * 2048;
;     const unsigned char* vsrc = Vimg + (size_t)h * 256 * SLOT + wid * 2048;
;     const unsigned lane16 = (unsigned)lane * 16u;
;     const unsigned kdst = lds0 + LDS_K + wid * 2048, vdst = lds0 + LDS_V + wid * 2048;
;     const unsigned short* Qw = Q + (size_t)(q0 + rg * 32 + r32) * AW + h * 128 + mp * 64 + hi * 8;
;     bf16x8 qr[4];
; #pragma unroll
;     for (int d0 = 0; d0 < 4; ++d0) qr[d0] = *(const bf16x8*)(Qw + d0 * 16);
;     int tj = t_lo;
;     ATT_DMA2(ksrc, tj, kdst); ATT_DMA2(ksrc, tj + 1, kdst + SLOT); ATT_DMA2(vsrc, tj, vdst); ATT_DMA2(ksrc, tj + 2, kdst + 2 * SLOT); ATT_DMA2(ksrc, tj + 3, kdst + 3 * SLOT); ATT_DMA2(vsrc, tj + 1, vdst + SLOT);
.LBB0_407:
	s_lshl_b32 s5, s74, 2
	s_add_i32 s5, s5, 0
	s_add_i32 s5, s5, 0x22000
	v_mov_b32_e32 v2, s5
	ds_read_b32 v2, v2
	v_readfirstlane_b32 s4, v0
	s_lshr_b32 s1, s4, 6
	s_bfe_u32 s0, s4, 0x10006
	v_mov_b32_e32 v205, v199
	s_waitcnt lgkmcnt(0)
	v_readfirstlane_b32 s5, v2
	s_bfe_u32 s14, s5, 0x60001
	s_and_b32 s10, s5, 0x1ff
	s_and_b32 s11, s5, 1
	s_xor_b32 s15, s14, 63
	s_or_b32 s14, s14, 64
	s_cmp_eq_u32 s11, 0
	s_cselect_b32 s11, s14, s15
	s_lshl_b32 s10, s10, 1
	s_add_i32 s10, s10, 0
	s_add_i32 s10, s10, 0x23880
	v_mov_b32_e32 v2, s10
	ds_read_u16 v2, v2
	s_lshl_b32 s80, s11, 7
	s_bfe_u32 s79, s5, 0x2000c
	v_cvt_f32_ubyte0_e32 v3, s79
	v_rcp_iflag_f32_e32 v4, v3
	s_waitcnt lgkmcnt(0)
	v_readfirstlane_b32 s10, v2
	s_and_b32 s10, s10, 0xffff
	s_sub_i32 s11, s80, s10
	s_add_i32 s10, s10, s80
	s_addk_i32 s10, 0x7f
	s_max_i32 s11, s11, 0
	s_min_u32 s10, s10, 0x3fff
	s_lshr_b32 s31, s11, 6
	s_lshr_b32 s75, s10, 6
	s_sub_i32 s10, s75, s31
	s_add_i32 s18, s10, 1
	v_cvt_f32_i32_e32 v2, s18
	s_bfe_u32 s14, s5, 0x20007
	s_xor_b32 s15, s14, 3
	s_lshl_b32 s14, s14, 1
	v_mul_f32_e32 v4, v2, v4
	v_trunc_f32_e32 v4, v4
	v_fma_f32 v2, -v4, v3, v2
	v_cvt_i32_f32_e32 v4, v4
	s_ashr_i32 s10, s18, 30
	s_bfe_u32 s5, s5, 0x2000a
	s_or_b32 s14, s14, -8
	s_or_b32 s19, s10, 1
	v_cmp_ge_f32_e64 s[10:11], |v2|, v3
	s_and_b64 s[10:11], s[10:11], exec
	s_cselect_b32 s10, s19, 0
	v_readfirstlane_b32 s11, v4
	s_add_i32 s11, s11, s10
	s_sext_i32_i16 s19, s11
	s_mul_i32 s79, s79, s19
	s_mul_i32 s77, s5, s19
	s_sub_i32 s18, s18, s79
	s_add_i32 s24, s31, s77
	s_cmp_lt_i32 s5, s18
	s_cselect_b64 s[10:11], -1, 0
	s_min_i32 s18, s5, s18
	s_add_i32 s30, s24, s18
	s_cmp_lg_u64 s[10:11], 0
	s_addc_u32 s10, s19, s30
	s_add_i32 s10, s10, -1
	s_lshl_b32 s18, s15, 22
	s_lshl_b32 s1, s1, 11
	s_add_u32 s11, s66, s18
	s_addc_u32 s19, s67, 0
	s_add_u32 s11, s11, s1
	s_addc_u32 s24, s19, 0
	s_cmp_lg_u32 0, -1
	s_cselect_b32 s19, 0, 0
	s_add_i32 s25, s1, s19
	s_lshr_b32 s19, s4, 2
	s_and_b32 s19, s19, 0x3fffffe0
	s_add_i32 s80, s80, s19
	v_or_b32_e32 v198, s80, v208
	v_lshlrev_b64 v[2:3], 10, v[198:199]
	v_lshl_add_u64 v[2:3], s[28:29], 0, v[2:3]
	s_lshl_b32 s96, s15, 8
	v_lshl_add_u64 v[2:3], v[2:3], 0, s[96:97]
	s_lshl_b32 s96, s0, 7
	v_lshl_add_u64 v[2:3], v[2:3], 0, s[96:97]
	v_lshl_add_u64 v[2:3], v[2:3], 0, v[204:205]
	global_load_dwordx4 v[130:133], v[2:3], off
	global_load_dwordx4 v[134:137], v[2:3], off offset:32
	global_load_dwordx4 v[138:141], v[2:3], off offset:64
	global_load_dwordx4 v[142:145], v[2:3], off offset:96
	v_ldexp_f32 v2, 1.0, s14
	s_add_u32 s14, s48, s18
	s_addc_u32 s15, s49, 0
	s_add_u32 s59, s14, s1
	s_addc_u32 s68, s15, 0
	s_min_i32 s14, s30, s10
	s_ashr_i32 s15, s14, 31
	s_add_i32 s58, s25, 0x10000
	s_lshl_b64 s[14:15], s[14:15], 14
	s_add_u32 s18, s59, s14
	s_addc_u32 s19, s68, s15
	s_add_i32 s1, s25, 0x400
	s_mov_b32 s60, m0
	s_mov_b32 m0, s25
	s_nop 0
	global_load_lds_dwordx4 v210, s[18:19]
	s_nop 0
	s_mov_b32 m0, s1
	s_nop 0
	global_load_lds_dwordx4 v211, s[18:19]
	s_nop 0
	s_mov_b32 m0, s60
	s_add_i32 s1, s30, 1
	s_min_i32 s18, s1, s10
	s_ashr_i32 s19, s18, 31
	s_lshl_b64 s[18:19], s[18:19], 14
	s_add_u32 s82, s59, s18
	s_addc_u32 s83, s68, s19
	s_add_i32 s1, s25, 0x4000
	s_add_i32 s60, s25, 0x4400
	s_add_u32 s14, s11, s14
	s_mov_b32 s61, m0
	s_mov_b32 m0, s1
	s_nop 0
	global_load_lds_dwordx4 v210, s[82:83]
	s_nop 0
	s_mov_b32 m0, s60
	s_nop 0
	global_load_lds_dwordx4 v211, s[82:83]
	s_nop 0
	s_mov_b32 m0, s61
	s_addc_u32 s15, s24, s15
	s_add_i32 s1, s25, 0x10400
	s_mov_b32 s60, m0
	s_mov_b32 m0, s58
	s_nop 0
	global_load_lds_dwordx4 v210, s[14:15]
	s_nop 0
	s_mov_b32 m0, s1
	s_nop 0
	global_load_lds_dwordx4 v211, s[14:15]
	s_nop 0
	s_mov_b32 m0, s60
	s_add_i32 s1, s30, 2
	s_min_i32 s14, s1, s10
	s_ashr_i32 s15, s14, 31
	s_lshl_b64 s[14:15], s[14:15], 14
	s_add_u32 s14, s59, s14
	s_addc_u32 s15, s68, s15
	s_add_i32 s1, s25, 0x8000
	s_add_i32 s60, s25, 0x8400
	s_mov_b32 s61, m0
	s_mov_b32 m0, s1
	s_nop 0
	global_load_lds_dwordx4 v210, s[14:15]
	s_nop 0
	s_mov_b32 m0, s60
	s_nop 0
	global_load_lds_dwordx4 v211, s[14:15]
	s_nop 0
	s_mov_b32 m0, s61
	s_add_i32 s1, s30, 3
	s_min_i32 s14, s1, s10
	s_ashr_i32 s15, s14, 31
	v_mul_f32_e32 v158, 0x3fb8aa3b, v2
	s_lshl_b64 s[14:15], s[14:15], 14
	v_lshl_or_b32 v2, s30, 6, v214
	s_add_u32 s14, s59, s14
	v_sub_u32_e32 v2, v198, v2
	s_addc_u32 s15, s68, s15
	s_add_i32 s1, s25, 0xc000
	s_add_i32 s60, s25, 0xc400
	v_cvt_f32_i32_e32 v2, v2
	s_mov_b32 s61, m0
	s_mov_b32 m0, s1
	s_nop 0
	global_load_lds_dwordx4 v210, s[14:15]
	s_nop 0
	s_mov_b32 m0, s60
	s_nop 0
	global_load_lds_dwordx4 v211, s[14:15]
	s_nop 0
	s_mov_b32 m0, s61
	s_add_u32 s14, s11, s18
	s_addc_u32 s15, s24, s19
	s_add_i32 s1, s25, 0x14000
	s_add_i32 s18, s25, 0x14400
	s_mov_b32 s19, m0
	s_mov_b32 m0, s1
	s_nop 0
	global_load_lds_dwordx4 v210, s[14:15]
	s_nop 0
	s_mov_b32 m0, s18
	s_nop 0
	global_load_lds_dwordx4 v211, s[14:15]
	s_nop 0
	s_mov_b32 m0, s19
	v_lshl_add_u32 v159, s0, 13, v212
	s_mov_b32 s0, -2.0
	s_mov_b32 s14, 0xc1000000
	s_mov_b32 s18, 0xc1200000
	s_mov_b32 s60, 0xc1800000
	s_mov_b32 s82, 0xc1900000
	s_mov_b32 s84, 0xc1c00000
	s_mov_b32 s86, 0xc1d00000
	v_add_f32_e32 v3, -1.0, v2
	s_mov_b32 s1, 0xc0400000
	s_mov_b32 s15, 0xc1100000
	s_mov_b32 s19, 0xc1300000
	s_mov_b32 s61, 0xc1880000
	s_mov_b32 s83, 0xc1980000
	s_mov_b32 s85, 0xc1c80000
	s_mov_b32 s87, 0xc1d80000
	s_mov_b64 vcc, s[66:67]
	v_pk_add_f32 v[4:5], v[2:3], s[0:1] op_sel_hi:[0,1]
	v_pk_add_f32 v[6:7], v[2:3], s[14:15] op_sel_hi:[0,1]
	v_pk_add_f32 v[8:9], v[2:3], s[18:19] op_sel_hi:[0,1]
	v_pk_add_f32 v[10:11], v[2:3], s[60:61] op_sel_hi:[0,1]
; #define ATT_WAIT_BAR(N) asm volatile("s_waitcnt vmcnt(" #N ") lgkmcnt(0)\n\ts_barrier" ::: "memory")
; __device__ __forceinline__ void bias_general(f32x16& p0, f32x16& p1, float dq, float nslope2, float shift2) {
; #pragma unroll
;     for (int r = 0; r < 16; ++r) { const float c = (float)((r & 3) + 8 * (r >> 2)); p0[r] = __builtin_fmaf(nslope2, __builtin_fabsf(dq - c), -shift2); p1[r] = __builtin_fmaf(nslope2, __builtin_fabsf(dq - (c + 32.f)), -shift2); }
; }
; __device__ __forceinline__ void attn_unit(int idx, float Bn, float Cn, float lam, const __attribute__((address_space(3))) unsigned short* pre, const __attribute__((address_space(3))) unsigned short* sidx, ...
;     ...
;     bias_general(sA0, sA1, dq0, nslope2, shift2);
;     bias_general(sB0, sB1, dq0 - 64.f, nslope2, shift2);
;     ATT_WAIT_BAR(8);
	v_pk_add_f32 v[12:13], v[2:3], s[82:83] op_sel_hi:[0,1]
	v_pk_add_f32 v[14:15], v[2:3], s[84:85] op_sel_hi:[0,1]
	v_pk_add_f32 v[16:17], v[2:3], s[86:87] op_sel_hi:[0,1]
	s_mov_b32 s88, 0xc2680000
	s_mov_b32 s90, 0xc2600000
	s_mov_b32 s62, 0xc2480000
	s_mov_b32 s12, 0xc2280000
	s_mov_b32 s8, 0xc2200000
	s_mov_b32 s66, 0xc2080000
	v_and_b32_e32 v5, 0x7fffffff, v5
	v_and_b32_e32 v4, 0x7fffffff, v4
	v_and_b32_e32 v7, 0x7fffffff, v7
	v_and_b32_e32 v6, 0x7fffffff, v6
	v_and_b32_e32 v9, 0x7fffffff, v9
	v_and_b32_e32 v8, 0x7fffffff, v8
	v_and_b32_e32 v11, 0x7fffffff, v11
	v_and_b32_e32 v10, 0x7fffffff, v10
	v_and_b32_e32 v13, 0x7fffffff, v13
	v_and_b32_e32 v12, 0x7fffffff, v12
	v_and_b32_e32 v15, 0x7fffffff, v15
	v_and_b32_e32 v14, 0x7fffffff, v14
	v_and_b32_e32 v17, 0x7fffffff, v17
	v_and_b32_e32 v16, 0x7fffffff, v16
	v_mov_b32_e32 v201, v200
	s_mov_b32 s89, 0xc26c0000
	s_mov_b32 s91, 0xc2640000
	s_mov_b32 s63, 0xc24c0000
	s_mov_b32 s13, 0xc22c0000
	s_mov_b32 s9, 0xc2240000
	s_mov_b32 s67, 0xc20c0000
	v_pk_fma_f32 v[48:49], v[158:159], v[16:17], v[200:201] op_sel_hi:[0,1,1] neg_lo:[1,0,0] neg_hi:[1,0,0]
	v_pk_fma_f32 v[46:47], v[158:159], v[14:15], v[200:201] op_sel_hi:[0,1,1] neg_lo:[1,0,0] neg_hi:[1,0,0]
	v_pk_fma_f32 v[44:45], v[158:159], v[12:13], v[200:201] op_sel_hi:[0,1,1] neg_lo:[1,0,0] neg_hi:[1,0,0]
	v_pk_fma_f32 v[42:43], v[158:159], v[10:11], v[200:201] op_sel_hi:[0,1,1] neg_lo:[1,0,0] neg_hi:[1,0,0]
	v_pk_fma_f32 v[40:41], v[158:159], v[8:9], v[200:201] op_sel_hi:[0,1,1] neg_lo:[1,0,0] neg_hi:[1,0,0]
	v_pk_fma_f32 v[38:39], v[158:159], v[6:7], v[200:201] op_sel_hi:[0,1,1] neg_lo:[1,0,0] neg_hi:[1,0,0]
	v_pk_fma_f32 v[36:37], v[158:159], v[4:5], v[200:201] op_sel_hi:[0,1,1] neg_lo:[1,0,0] neg_hi:[1,0,0]
	v_pk_add_f32 v[4:5], v[2:3], s[88:89] op_sel_hi:[0,1]
	v_pk_add_f32 v[6:7], v[2:3], s[90:91] op_sel_hi:[0,1]
	v_pk_add_f32 v[8:9], v[2:3], s[62:63] op_sel_hi:[0,1]
	v_pk_add_f32 v[10:11], v[2:3], s[64:65] op_sel_hi:[0,1]
	v_pk_add_f32 v[12:13], v[2:3], s[12:13] op_sel_hi:[0,1]
	v_pk_add_f32 v[14:15], v[2:3], s[8:9] op_sel_hi:[0,1]
	v_pk_add_f32 v[16:17], v[2:3], s[66:67] op_sel_hi:[0,1]
	v_and_b32_e32 v18, 0x7fffffff, v2
	v_and_b32_e32 v19, 0x7fffffff, v3
	v_and_b32_e32 v17, 0x7fffffff, v17
	v_and_b32_e32 v16, 0x7fffffff, v16
	v_and_b32_e32 v15, 0x7fffffff, v15
	v_and_b32_e32 v14, 0x7fffffff, v14
	v_and_b32_e32 v13, 0x7fffffff, v13
	v_and_b32_e32 v12, 0x7fffffff, v12
	v_and_b32_e32 v11, 0x7fffffff, v11
	v_and_b32_e32 v10, 0x7fffffff, v10
	v_and_b32_e32 v9, 0x7fffffff, v9
	v_and_b32_e32 v8, 0x7fffffff, v8
	v_and_b32_e32 v7, 0x7fffffff, v7
	v_and_b32_e32 v6, 0x7fffffff, v6
	v_and_b32_e32 v5, 0x7fffffff, v5
	v_and_b32_e32 v4, 0x7fffffff, v4
	v_add_f32_e32 v154, 0xc2800000, v2
	v_pk_fma_f32 v[34:35], v[158:159], v[18:19], v[202:203] op_sel_hi:[0,1,1] neg_lo:[1,0,0] neg_hi:[1,0,0]
	v_pk_add_f32 v[18:19], v[2:3], s[54:55] op_sel_hi:[0,1]
	v_pk_fma_f32 v[64:65], v[158:159], v[4:5], v[200:201] op_sel_hi:[0,1,1] neg_lo:[1,0,0] neg_hi:[1,0,0]
	v_pk_fma_f32 v[62:63], v[158:159], v[6:7], v[200:201] op_sel_hi:[0,1,1] neg_lo:[1,0,0] neg_hi:[1,0,0]
	v_pk_fma_f32 v[60:61], v[158:159], v[8:9], v[200:201] op_sel_hi:[0,1,1] neg_lo:[1,0,0] neg_hi:[1,0,0]
	v_pk_fma_f32 v[58:59], v[158:159], v[10:11], v[200:201] op_sel_hi:[0,1,1] neg_lo:[1,0,0] neg_hi:[1,0,0]
	v_pk_fma_f32 v[56:57], v[158:159], v[12:13], v[200:201] op_sel_hi:[0,1,1] neg_lo:[1,0,0] neg_hi:[1,0,0]
	v_pk_fma_f32 v[54:55], v[158:159], v[14:15], v[200:201] op_sel_hi:[0,1,1] neg_lo:[1,0,0] neg_hi:[1,0,0]
	v_pk_fma_f32 v[52:53], v[158:159], v[16:17], v[200:201] op_sel_hi:[0,1,1] neg_lo:[1,0,0] neg_hi:[1,0,0]
	v_add_f32_e32 v17, -1.0, v154
	v_pk_add_f32 v[2:3], v[154:155], s[0:1] op_sel_hi:[0,1]
	v_pk_add_f32 v[4:5], v[154:155], s[14:15] op_sel_hi:[0,1]
	v_pk_add_f32 v[6:7], v[154:155], s[18:19] op_sel_hi:[0,1]
	v_pk_add_f32 v[8:9], v[154:155], s[60:61] op_sel_hi:[0,1]
	v_pk_add_f32 v[10:11], v[154:155], s[82:83] op_sel_hi:[0,1]
	v_pk_add_f32 v[12:13], v[154:155], s[84:85] op_sel_hi:[0,1]
	v_pk_add_f32 v[14:15], v[154:155], s[86:87] op_sel_hi:[0,1]
	v_and_b32_e32 v19, 0x7fffffff, v19
	v_and_b32_e32 v18, 0x7fffffff, v18
	v_and_b32_e32 v3, 0x7fffffff, v3
	v_and_b32_e32 v2, 0x7fffffff, v2
	v_and_b32_e32 v5, 0x7fffffff, v5
	v_and_b32_e32 v4, 0x7fffffff, v4
	v_and_b32_e32 v7, 0x7fffffff, v7
	v_and_b32_e32 v6, 0x7fffffff, v6
	v_and_b32_e32 v9, 0x7fffffff, v9
	v_and_b32_e32 v8, 0x7fffffff, v8
	v_and_b32_e32 v11, 0x7fffffff, v11
	v_and_b32_e32 v10, 0x7fffffff, v10
	v_and_b32_e32 v13, 0x7fffffff, v13
	v_and_b32_e32 v12, 0x7fffffff, v12
	v_and_b32_e32 v15, 0x7fffffff, v15
	v_and_b32_e32 v14, 0x7fffffff, v14
	v_and_b32_e32 v16, 0x7fffffff, v154
	v_and_b32_e32 v17, 0x7fffffff, v17
	v_pk_fma_f32 v[50:51], v[158:159], v[18:19], v[202:203] op_sel_hi:[0,1,1] neg_lo:[1,0,0] neg_hi:[1,0,0]
	v_pk_fma_f32 v[18:19], v[158:159], v[16:17], v[202:203] op_sel_hi:[0,1,1] neg_lo:[1,0,0] neg_hi:[1,0,0]
	v_pk_fma_f32 v[32:33], v[158:159], v[14:15], v[200:201] op_sel_hi:[0,1,1] neg_lo:[1,0,0] neg_hi:[1,0,0]
	v_pk_fma_f32 v[30:31], v[158:159], v[12:13], v[200:201] op_sel_hi:[0,1,1] neg_lo:[1,0,0] neg_hi:[1,0,0]
	v_pk_fma_f32 v[28:29], v[158:159], v[10:11], v[200:201] op_sel_hi:[0,1,1] neg_lo:[1,0,0] neg_hi:[1,0,0]
	v_pk_fma_f32 v[26:27], v[158:159], v[8:9], v[200:201] op_sel_hi:[0,1,1] neg_lo:[1,0,0] neg_hi:[1,0,0]
	v_pk_fma_f32 v[24:25], v[158:159], v[6:7], v[200:201] op_sel_hi:[0,1,1] neg_lo:[1,0,0] neg_hi:[1,0,0]
	v_pk_fma_f32 v[22:23], v[158:159], v[4:5], v[200:201] op_sel_hi:[0,1,1] neg_lo:[1,0,0] neg_hi:[1,0,0]
	v_pk_fma_f32 v[20:21], v[158:159], v[2:3], v[200:201] op_sel_hi:[0,1,1] neg_lo:[1,0,0] neg_hi:[1,0,0]
	v_pk_add_f32 v[2:3], v[154:155], s[88:89] op_sel_hi:[0,1]
	v_pk_add_f32 v[4:5], v[154:155], s[90:91] op_sel_hi:[0,1]
	v_pk_add_f32 v[6:7], v[154:155], s[62:63] op_sel_hi:[0,1]
	v_pk_add_f32 v[8:9], v[154:155], s[64:65] op_sel_hi:[0,1]
	v_pk_add_f32 v[10:11], v[154:155], s[12:13] op_sel_hi:[0,1]
	v_pk_add_f32 v[12:13], v[154:155], s[8:9] op_sel_hi:[0,1]
	v_pk_add_f32 v[14:15], v[154:155], s[66:67] op_sel_hi:[0,1]
	v_pk_add_f32 v[16:17], v[154:155], s[54:55] op_sel_hi:[0,1]
	v_and_b32_e32 v67, 0x7fffffff, v17
	v_and_b32_e32 v66, 0x7fffffff, v16
	v_and_b32_e32 v69, 0x7fffffff, v15
	v_and_b32_e32 v68, 0x7fffffff, v14
	v_and_b32_e32 v71, 0x7fffffff, v13
	v_and_b32_e32 v70, 0x7fffffff, v12
	v_and_b32_e32 v73, 0x7fffffff, v11
	v_and_b32_e32 v72, 0x7fffffff, v10
	v_and_b32_e32 v9, 0x7fffffff, v9
	v_and_b32_e32 v8, 0x7fffffff, v8
	v_and_b32_e32 v7, 0x7fffffff, v7
	v_and_b32_e32 v6, 0x7fffffff, v6
	v_and_b32_e32 v5, 0x7fffffff, v5
	v_and_b32_e32 v4, 0x7fffffff, v4
	v_and_b32_e32 v3, 0x7fffffff, v3
	v_and_b32_e32 v2, 0x7fffffff, v2
	s_waitcnt vmcnt(8) lgkmcnt(0)
	s_barrier
; __device__ __forceinline__ unsigned cvtpk(float lo, float hi) { unsigned r; asm volatile("v_cvt_pk_bf16_f32 %0, %1, %2" : "=v"(r) : "v"(lo), "v"(hi)); return r; }
; __device__ __forceinline__ void qkt_acc(f32x16& p0, f32x16& p1, lds_cptr kp, const bf16x8* qr) {
; #pragma unroll
;     for (int d0 = 0; d0 < 4; ++d0) {
;         const bf16x8 b0 = *(const __attribute__((address_space(3))) bf16x8*)(kp + d0 * 2048);
;         const bf16x8 b1 = *(const __attribute__((address_space(3))) bf16x8*)(kp + d0 * 2048 + 512);
;         p0 = __builtin_amdgcn_mfma_f32_32x32x16_bf16(b0, qr[d0], p0, 0, 0, 0);
;         p1 = __builtin_amdgcn_mfma_f32_32x32x16_bf16(b1, qr[d0], p1, 0, 0, 0);
;     }
; }
; __device__ __forceinline__ void bias_general(f32x16& p0, f32x16& p1, float dq, float nslope2, float shift2) {
; #pragma unroll
;     for (int r = 0; r < 16; ++r) { const float c = (float)((r & 3) + 8 * (r >> 2)); p0[r] = __builtin_fmaf(nslope2, __builtin_fabsf(dq - c), -shift2); p1[r] = __builtin_fmaf(nslope2, __builtin_fabsf(dq - (c + 32.f)), -shift2); }
; }
; __device__ __forceinline__ void softmax_first(f32x16& p0, f32x16& p1, bf16x8& pa0, bf16x8& pa1, bf16x8& pa2) {
; #pragma unroll
;     for (int r = 0; r < 16; ++r) { p0[r] = __builtin_amdgcn_exp2f(p0[r]); p1[r] = __builtin_amdgcn_exp2f(p1[r]); }
;     { u32x4 w = {cvtpk(p0[0], p0[1]), cvtpk(p0[2], p0[3]), cvtpk(p0[4], p0[5]), cvtpk(p0[6], p0[7])}; pa0 = __builtin_bit_cast(bf16x8, w); }
;     { u32x4 w = {cvtpk(p0[8], p0[9]), cvtpk(p0[10], p0[11]), cvtpk(p0[12], p0[13]), cvtpk(p0[14], p0[15])}; pa1 = __builtin_bit_cast(bf16x8, w); }
;     { u32x4 w = {cvtpk(p1[0], p1[1]), cvtpk(p1[2], p1[3]), cvtpk(p1[4], p1[5]), cvtpk(p1[6], p1[7])}; pa2 = __builtin_bit_cast(bf16x8, w); }
; }
; __device__ __forceinline__ void attn_unit(int idx, float Bn, float Cn, float lam, const __attribute__((address_space(3))) unsigned short* pre, const __attribute__((address_space(3))) unsigned short* sidx, ...
;     ...
;     qkt_acc(sA0, sA1, kp0, qr);
;     qkt_acc(sB0, sB1, kp0 + SLOT, qr);
;     softmax_first(sA0, sA1, pa0, pa1, pa2);
;     float dq1 = dq0 - 64.f;
;     int sk_cur = 2 * SLOT, sv_cur = 0, sk_dma = 0, sv_dma = 2 * SLOT;
;     const bool lead_half = wid < 4;
;     if (wid >= 4) __builtin_amdgcn_s_setprio(1);
	v_pk_fma_f32 v[16:17], v[158:159], v[2:3], v[200:201] op_sel_hi:[0,1,1] neg_lo:[1,0,0] neg_hi:[1,0,0]
	v_pk_fma_f32 v[14:15], v[158:159], v[4:5], v[200:201] op_sel_hi:[0,1,1] neg_lo:[1,0,0] neg_hi:[1,0,0]
	v_pk_fma_f32 v[12:13], v[158:159], v[6:7], v[200:201] op_sel_hi:[0,1,1] neg_lo:[1,0,0] neg_hi:[1,0,0]
	v_pk_fma_f32 v[10:11], v[158:159], v[8:9], v[200:201] op_sel_hi:[0,1,1] neg_lo:[1,0,0] neg_hi:[1,0,0]
	v_pk_fma_f32 v[8:9], v[158:159], v[72:73], v[200:201] op_sel_hi:[0,1,1] neg_lo:[1,0,0] neg_hi:[1,0,0]
	v_pk_fma_f32 v[6:7], v[158:159], v[70:71], v[200:201] op_sel_hi:[0,1,1] neg_lo:[1,0,0] neg_hi:[1,0,0]
	v_pk_fma_f32 v[4:5], v[158:159], v[68:69], v[200:201] op_sel_hi:[0,1,1] neg_lo:[1,0,0] neg_hi:[1,0,0]
	v_pk_fma_f32 v[2:3], v[158:159], v[66:67], v[202:203] op_sel_hi:[0,1,1] neg_lo:[1,0,0] neg_hi:[1,0,0]
	ds_read_b128 v[66:69], v159
	ds_read_b128 v[70:73], v159 offset:512
	s_waitcnt vmcnt(3) lgkmcnt(1)
	v_mfma_f32_32x32x16_bf16 v[34:49], v[66:69], v[130:133], v[34:49]
	s_cmpk_lt_u32 s4, 0x100
	s_waitcnt lgkmcnt(0)
	v_mfma_f32_32x32x16_bf16 v[50:65], v[70:73], v[130:133], v[50:65]
	ds_read_b128 v[66:69], v159 offset:2048
	ds_read_b128 v[70:73], v159 offset:2560
	s_waitcnt vmcnt(2) lgkmcnt(1)
	v_mfma_f32_32x32x16_bf16 v[34:49], v[66:69], v[134:137], v[34:49]
	s_waitcnt lgkmcnt(0)
	v_mfma_f32_32x32x16_bf16 v[50:65], v[70:73], v[134:137], v[50:65]
	ds_read_b128 v[66:69], v159 offset:4096
	ds_read_b128 v[70:73], v159 offset:4608
	s_waitcnt vmcnt(1) lgkmcnt(1)
	v_mfma_f32_32x32x16_bf16 v[34:49], v[66:69], v[138:141], v[34:49]
	s_waitcnt lgkmcnt(0)
	v_mfma_f32_32x32x16_bf16 v[50:65], v[70:73], v[138:141], v[50:65]
	ds_read_b128 v[66:69], v159 offset:6144
	ds_read_b128 v[70:73], v159 offset:6656
	s_waitcnt vmcnt(0) lgkmcnt(1)
	v_mfma_f32_32x32x16_bf16 v[34:49], v[66:69], v[142:145], v[34:49]
	s_waitcnt lgkmcnt(0)
	v_mfma_f32_32x32x16_bf16 v[50:65], v[70:73], v[142:145], v[50:65]
	ds_read_b128 v[66:69], v159 offset:16384
	ds_read_b128 v[70:73], v159 offset:16896
	s_nop 7
	v_exp_f32_e32 v34, v34
	v_exp_f32_e32 v35, v35
	v_exp_f32_e32 v36, v36
	v_exp_f32_e32 v37, v37
	v_exp_f32_e32 v38, v38
	v_exp_f32_e32 v39, v39
	s_waitcnt lgkmcnt(1)
	v_mfma_f32_32x32x16_bf16 v[18:33], v[66:69], v[130:133], v[18:33]
	v_exp_f32_e32 v50, v50
	v_exp_f32_e32 v51, v51
	v_exp_f32_e32 v52, v52
	v_exp_f32_e32 v53, v53
	v_exp_f32_e32 v54, v54
	v_exp_f32_e32 v55, v55
	v_exp_f32_e32 v40, v40
	s_waitcnt lgkmcnt(0)
	v_mfma_f32_32x32x16_bf16 v[2:17], v[70:73], v[130:133], v[2:17]
	ds_read_b128 v[66:69], v159 offset:18432
	ds_read_b128 v[70:73], v159 offset:18944
	v_exp_f32_e32 v56, v56
	v_exp_f32_e32 v41, v41
	v_exp_f32_e32 v57, v57
	v_exp_f32_e32 v42, v42
	v_exp_f32_e32 v43, v43
	v_exp_f32_e32 v44, v44
	s_waitcnt lgkmcnt(1)
	v_mfma_f32_32x32x16_bf16 v[18:33], v[66:69], v[134:137], v[18:33]
	v_exp_f32_e32 v45, v45
	v_exp_f32_e32 v46, v46
	v_exp_f32_e32 v47, v47
	v_exp_f32_e32 v48, v48
	v_exp_f32_e32 v49, v49
	s_waitcnt lgkmcnt(0)
	v_mfma_f32_32x32x16_bf16 v[2:17], v[70:73], v[134:137], v[2:17]
	ds_read_b128 v[66:69], v159 offset:20480
	ds_read_b128 v[70:73], v159 offset:20992
	s_waitcnt lgkmcnt(1)
	v_mfma_f32_32x32x16_bf16 v[18:33], v[66:69], v[138:141], v[18:33]
	s_waitcnt lgkmcnt(0)
	v_mfma_f32_32x32x16_bf16 v[2:17], v[70:73], v[138:141], v[2:17]
	ds_read_b128 v[66:69], v159 offset:22528
	ds_read_b128 v[70:73], v159 offset:23040
	v_cvt_pk_bf16_f32 v170, v34, v35
	v_cvt_pk_bf16_f32 v171, v36, v37
	v_cvt_pk_bf16_f32 v172, v38, v39
	v_cvt_pk_bf16_f32 v173, v40, v41
	v_cvt_pk_bf16_f32 v166, v42, v43
	v_cvt_pk_bf16_f32 v167, v44, v45
	s_waitcnt lgkmcnt(1)
	v_mfma_f32_32x32x16_bf16 v[18:33], v[66:69], v[142:145], v[18:33]
	v_cvt_pk_bf16_f32 v168, v46, v47
	v_cvt_pk_bf16_f32 v169, v48, v49
	v_cvt_pk_bf16_f32 v174, v50, v51
	v_cvt_pk_bf16_f32 v175, v52, v53
	v_cvt_pk_bf16_f32 v176, v54, v55
	v_cvt_pk_bf16_f32 v177, v56, v57
	s_waitcnt lgkmcnt(0)
	v_mfma_f32_32x32x16_bf16 v[2:17], v[70:73], v[142:145], v[2:17]
	s_cbranch_scc1 .LBB0_409
	s_setprio 3
